# chunk scan consumer prologue: the four ring-chunk loads are issued before the prologue barrier so their latency overlaps the loader waves' prologue
# baseline (speedup 1.0000x reference)
; #define LAS __attribute__((address_space(3)))
; #define WG_BAR() do { asm volatile("s_waitcnt lgkmcnt(0)" ::: "memory"); __builtin_amdgcn_s_barrier(); asm volatile("" ::: "memory"); } while (0)
; __device__ __forceinline__ int scan_item(int bh, int n) { if (n > NCH - 1) n = NCH - 1; return ((bh >> 2) * NCH + n) * 4 + (bh & 3); }
; __device__ __forceinline__ void scana_load(ScanA& p, const unsigned char* ws, int bh, int n, int td, int lane) {
;     const bf16* Ms = (const bf16*)(ws + WS_MS) + (size_t)scan_item(bh, n) * 16384 + td * 4096 + lane * 8;
; #pragma unroll
;     for (int q = 0; q < 8; ++q) p.a[q] = *(const bf16x8*)(Ms + 512 * q);
; }
; __device__ __forceinline__ void dn_scan(const Args& a, LAS unsigned char* lds, int wg, int tid, int wave, int lane) {
;     ...
;     const int bh = wg & 7, te = wg >> 3, td = wave & 3;
;     for (int u = tid; u < 2 * 8192 / 4; u += NTHR) ((LAS unsigned*)lds)[u] = 0u;
;     if (wave < 4) {
;         f32x16 acc = zero16();
;         ScanB p0, p1, p2, p3, p4, p5, p6, p7;
;         scanb_load(p0, ws, bh, 0, td, te, lane); scanb_load(p1, ws, bh, 1, td, te, lane); scanb_load(p2, ws, bh, 2, td, te, lane); scanb_load(p3, ws, bh, 3, td, te, lane);
;         scanb_load(p4, ws, bh, 4, td, te, lane); scanb_load(p5, ws, bh, 5, td, te, lane); scanb_load(p6, ws, bh, 6, td, te, lane);
;         WG_BAR();
.LBB0_1066:
	s_and_b64 vcc, exec, s[4:5]
	s_cbranch_vccz .LBB0_1069
	s_lshl_b32 s4, s2, 5
	s_and_b32 s12, s4, 0x80
	s_lshl_b32 s4, s12, 2
	s_and_b32 s13, s2, 3
	s_or_b32 s8, s4, s13
	s_add_u32 s4, s92, 0x1390000
	s_addc_u32 s5, s93, 0
	s_lshl_b32 s6, s8, 2
	s_add_u32 s9, s92, 0xcc00000
	s_waitcnt vmcnt(23)
	v_mov_b32_e32 v0, s6
	s_addc_u32 s10, s93, 0
	s_lshl_b32 s6, s8, 15
	s_add_u32 s6, s9, s6
	s_addc_u32 s7, s10, 0
	s_lshl_b32 s14, s2, 10
	s_lshl_b32 s11, s64, 11
	s_and_b32 s14, s14, 0x6000
	s_or_b32 s11, s11, s14
	s_add_u32 s6, s6, s11
	s_addc_u32 s7, s7, 0
	global_load_dwordx4 v[60:63], v128, s[6:7]
	global_load_dwordx4 v[56:59], v128, s[6:7] offset:1024
	s_or_b32 s6, s8, 4
	s_lshl_b32 s7, s6, 2
	s_lshl_b32 s6, s6, 15
	s_add_u32 s6, s9, s6
	v_mov_b32_e32 v1, s7
	s_addc_u32 s7, s10, 0
	s_add_u32 s6, s6, s11
	s_addc_u32 s7, s7, 0
	global_load_dwordx4 v[76:79], v128, s[6:7]
	global_load_dwordx4 v[68:71], v128, s[6:7] offset:1024
	s_or_b32 s6, s8, 8
	s_lshl_b32 s7, s6, 2
	s_lshl_b32 s6, s6, 15
	s_add_u32 s6, s9, s6
	v_mov_b32_e32 v2, s7
	s_addc_u32 s7, s10, 0
	s_add_u32 s6, s6, s11
	s_addc_u32 s7, s7, 0
	global_load_dwordx4 v[84:87], v128, s[6:7]
	global_load_dwordx4 v[80:83], v128, s[6:7] offset:1024
	s_or_b32 s6, s8, 12
	s_lshl_b32 s7, s6, 2
	s_lshl_b32 s6, s6, 15
	s_add_u32 s6, s9, s6
	v_mov_b32_e32 v3, s7
	s_addc_u32 s7, s10, 0
	s_add_u32 s6, s6, s11
	s_addc_u32 s7, s7, 0
	global_load_dwordx4 v[36:39], v128, s[6:7]
	global_load_dwordx4 v[32:35], v128, s[6:7] offset:1024
	s_or_b32 s6, s8, 16
	s_lshl_b32 s7, s6, 2
	s_lshl_b32 s6, s6, 15
	s_add_u32 s6, s9, s6
	s_waitcnt vmcnt(30)
	v_mov_b32_e32 v4, s7
	s_addc_u32 s7, s10, 0
	s_add_u32 s6, s6, s11
	s_addc_u32 s7, s7, 0
	global_load_dwordx4 v[44:47], v128, s[6:7]
	global_load_dwordx4 v[40:43], v128, s[6:7] offset:1024
	s_or_b32 s6, s8, 20
	s_lshl_b32 s7, s6, 2
	s_lshl_b32 s6, s6, 15
	s_add_u32 s6, s9, s6
	v_mov_b32_e32 v5, s7
	s_addc_u32 s7, s10, 0
	s_add_u32 s6, s6, s11
	s_addc_u32 s7, s7, 0
	global_load_dwordx4 v[52:55], v128, s[6:7]
	global_load_dwordx4 v[48:51], v128, s[6:7] offset:1024
	s_or_b32 s6, s8, 24
	s_lshl_b32 s7, s6, 2
	v_mov_b32_e32 v6, s7
	global_load_dword v126, v0, s[4:5]
	global_load_dword v124, v1, s[4:5]
	global_load_dword v122, v2, s[4:5]
	global_load_dword v114, v3, s[4:5]
	global_load_dword v116, v4, s[4:5]
	global_load_dword v118, v5, s[4:5]
	global_load_dword v120, v6, s[4:5]
	s_lshl_b32 s6, s6, 15
	s_add_u32 s6, s9, s6
	s_addc_u32 s7, s10, 0
	s_add_u32 s6, s6, s11
	s_addc_u32 s7, s7, 0
	global_load_dwordx4 v[72:75], v128, s[6:7]
	global_load_dwordx4 v[64:67], v128, s[6:7] offset:1024
	s_add_u32 s8, s9, s11
	s_addc_u32 s9, s10, 0
	s_lshl_b32 s6, s64, 13
	v_mov_b32_e32 v129, 0
	s_add_i32 s14, s6, 0
	s_mul_i32 s6, s64, 0xffffe800
	v_lshl_add_u64 v[96:97], s[8:9], 0, v[128:129]
	s_add_i32 s15, s14, s6
	s_mul_i32 s9, s64, 0x1800
	s_add_i32 s18, s15, s9
	s_bfe_u32 s9, s2, 0x10002
	s_lshl_b32 s8, s13, 15
	s_add_i32 s19, s18, s6
	s_lshl_b32 s6, s9, 24
	s_or_b32 s8, s6, s8
	s_mov_b32 s7, 0
	v_lshl_or_b32 v0, v200, 4, s11
	v_mov_b32_e32 v1, v129
	s_or_b32 s6, s8, 0xc0000
	v_lshl_add_u64 v[98:99], v[0:1], 0, s[6:7]
	s_or_b32 s6, s8, 0xa0000
	v_lshl_add_u64 v[100:101], v[0:1], 0, s[6:7]
	s_or_b32 s6, s8, 0x80000
	v_lshl_add_u64 v[102:103], v[0:1], 0, s[6:7]
	s_or_b32 s6, s8, 0x60000
	v_lshl_add_u64 v[104:105], v[0:1], 0, s[6:7]
	s_or_b32 s6, s8, 0x40000
	v_lshl_add_u64 v[106:107], v[0:1], 0, s[6:7]
	s_or_b32 s6, s8, 0x20000
	v_lshl_add_u64 v[108:109], v[0:1], 0, s[6:7]
	s_lshl_b32 s6, s9, 9
	s_or_b32 s6, s6, s13
	s_or_b32 s9, s6, 28
	s_bfe_u32 s98, s2, 0x10002
	s_lshl_b32 s98, s98, 24
	s_and_b32 s100, s2, 3
	s_lshl_b32 s100, s100, 15
	s_or_b32 s98, s98, s100
	s_lshl_b32 s100, s64, 13
	s_or_b32 s98, s98, s100
	s_add_u32 s98, s98, 0x2c00000
	s_add_u32 s100, s92, s98
	s_addc_u32 s101, s93, 0
	v_add_u32_e32 v147, 0x1000, v128
	global_load_dwordx4 v[148:151], v128, s[100:101] offset:2048
	global_load_dwordx4 v[152:155], v128, s[100:101] offset:3072
	global_load_dwordx4 v[156:159], v147, s[100:101]
	global_load_dwordx4 v[160:163], v147, s[100:101] offset:1024
	global_load_dwordx4 v[164:167], v147, s[100:101] offset:2048
	global_load_dwordx4 v[168:171], v147, s[100:101] offset:3072
	v_add_u32_e32 v146, 0x20000, v128
	v_add_u32_e32 v147, 0x21000, v128
	global_load_dwordx4 v[172:175], v146, s[100:101] offset:2048
	global_load_dwordx4 v[176:179], v146, s[100:101] offset:3072
	global_load_dwordx4 v[180:183], v147, s[100:101]
	global_load_dwordx4 v[184:187], v147, s[100:101] offset:1024
	global_load_dwordx4 v[188:191], v147, s[100:101] offset:2048
	global_load_dwordx4 v[192:195], v147, s[100:101] offset:3072
	v_add_u32_e32 v146, 0x40000, v128
	v_add_u32_e32 v147, 0x41000, v128
	global_load_dwordx4 v[196:199], v146, s[100:101] offset:2048
	global_load_dwordx4 v[208:211], v146, s[100:101] offset:3072
	global_load_dwordx4 v[212:215], v147, s[100:101]
	global_load_dwordx4 v[216:219], v147, s[100:101] offset:1024
	global_load_dwordx4 v[220:223], v147, s[100:101] offset:2048
	global_load_dwordx4 v[224:227], v147, s[100:101] offset:3072
	v_add_u32_e32 v146, 0x60000, v128
	v_add_u32_e32 v147, 0x61000, v128
	global_load_dwordx4 v[228:231], v146, s[100:101] offset:2048
	global_load_dwordx4 v[232:235], v146, s[100:101] offset:3072
	global_load_dwordx4 v[236:239], v147, s[100:101]
	global_load_dwordx4 v[240:243], v147, s[100:101] offset:1024
	global_load_dwordx4 v[244:247], v147, s[100:101] offset:2048
	global_load_dwordx4 v[248:251], v147, s[100:101] offset:3072
	s_waitcnt lgkmcnt(0)
	s_barrier
	s_lshl_b32 s6, s9, 2
	s_or_b32 s6, s6, 0x1390000
	s_lshl_b32 s10, s9, 15
	s_mov_b32 s11, s7
	s_mov_b32 s9, s7
	s_or_b32 s20, s12, 9
	s_add_i32 s21, s14, 0x14000
	s_or_b32 s22, s12, 10
	s_add_i32 s23, s14, 0x1c000
	s_or_b32 s24, s12, 11
	s_or_b32 s25, s12, 12
	s_or_b32 s26, s12, 13
	s_or_b32 s27, s12, 14
	v_lshl_add_u64 v[110:111], v[0:1], 0, s[10:11]
	v_lshl_add_u64 v[112:113], v[0:1], 0, s[8:9]
	s_mov_b32 s30, -8
	s_mov_b32 s28, 0xcc00000
	s_mov_b64 s[8:9], 0x100000
	s_mov_b64 s[10:11], s[6:7]
	v_mov_b32_e32 v0, 0
	v_mov_b32_e32 v2, 0
	v_mov_b32_e32 v3, v129
	v_mov_b32_e32 v4, 0
	v_mov_b32_e32 v5, v129
	v_mov_b32_e32 v6, 0
	v_mov_b32_e32 v7, v129
	s_waitcnt vmcnt(63)
	v_mov_b32_e32 v8, 0
	v_mov_b32_e32 v9, v129
	v_mov_b32_e32 v10, 0
	v_mov_b32_e32 v11, v129
	s_waitcnt vmcnt(63)
	v_mov_b32_e32 v12, 0
	v_mov_b32_e32 v13, v129
	v_mov_b32_e32 v14, 0
	v_mov_b32_e32 v15, v129
	s_waitcnt vmcnt(0)
